# stack14 variant: softmax VALU spread evenly (transcendentals weighted 2) over all 15 P.V MFMA gaps
# speedup vs baseline: 1.0100x; 1.0084x over previous
.Li0_sm:
	ds_read_b64_tr_b16 v[188:189], v158 offset:0x400
	ds_read_b64_tr_b16 v[190:191], v158 offset:0xc00
	ds_read_b64_tr_b16 v[192:193], v158 offset:0x600
	ds_read_b64_tr_b16 v[194:195], v158 offset:0xe00
	s_waitcnt lgkmcnt(6)
	v_mfma_f32_32x32x16_bf16 v[48:63], v[176:179], v[180:183], v[48:63]
	ds_read_b64_tr_b16 v[180:181], v158 offset:0x1000
	ds_read_b64_tr_b16 v[182:183], v158 offset:0x1800
	v_mul_f32_e32 v114, 0xbe0293ee, v166
	v_max_f32_e32 v112, v65, v65
	v_max_f32_e32 v113, v64, v64
	v_fmamk_f32 v64, v64, 0x3e0293ee, v114
	v_max_f32_e32 v112, v113, v112
	v_exp_f32_e32 v64, v64
	s_waitcnt lgkmcnt(6)
	v_mfma_f32_32x32x16_bf16 v[32:47], v[176:179], v[184:187], v[32:47]
	ds_read_b64_tr_b16 v[184:185], v158 offset:0x1200
	ds_read_b64_tr_b16 v[186:187], v158 offset:0x1a00
	v_fmamk_f32 v65, v65, 0x3e0293ee, v114
	v_max3_f32 v112, v112, v66, v67
	v_exp_f32_e32 v65, v65
	v_fmamk_f32 v66, v66, 0x3e0293ee, v114
	v_exp_f32_e32 v66, v66
	s_waitcnt lgkmcnt(6)
	v_mfma_f32_32x32x16_bf16 v[16:31], v[176:179], v[188:191], v[16:31]
	ds_read_b64_tr_b16 v[188:189], v158 offset:0x1400
	ds_read_b64_tr_b16 v[190:191], v158 offset:0x1c00
	v_fmamk_f32 v67, v67, 0x3e0293ee, v114
	v_max3_f32 v112, v112, v68, v69
	v_exp_f32_e32 v67, v67
	v_fmamk_f32 v68, v68, 0x3e0293ee, v114
	v_add_f32_e32 v115, 0, v64
	s_waitcnt lgkmcnt(6)
	v_mfma_f32_32x32x16_bf16 v[0:15], v[176:179], v[192:195], v[0:15]
	ds_read_b64_tr_b16 v[192:193], v158 offset:0x1600
	ds_read_b64_tr_b16 v[194:195], v158 offset:0x1e00
	v_exp_f32_e32 v68, v68
	v_fmamk_f32 v69, v69, 0x3e0293ee, v114
	v_max3_f32 v112, v112, v70, v71
	v_add_f32_e32 v115, v65, v115
	v_exp_f32_e32 v69, v69
	s_waitcnt lgkmcnt(6)
	v_mfma_f32_32x32x16_bf16 v[48:63], v[124:127], v[180:183], v[48:63]
	ds_read_b64_tr_b16 v[180:181], v158 offset:0x2000
	ds_read_b64_tr_b16 v[182:183], v158 offset:0x2800
	v_fmamk_f32 v70, v70, 0x3e0293ee, v114
	v_add_f32_e32 v115, v66, v115
	v_exp_f32_e32 v70, v70
	v_fmamk_f32 v71, v71, 0x3e0293ee, v114
	v_max3_f32 v112, v112, v72, v73
	s_waitcnt lgkmcnt(6)
	v_mfma_f32_32x32x16_bf16 v[32:47], v[124:127], v[184:187], v[32:47]
	ds_read_b64_tr_b16 v[184:185], v158 offset:0x2200
	ds_read_b64_tr_b16 v[186:187], v158 offset:0x2a00
	v_add_f32_e32 v115, v67, v115
	v_exp_f32_e32 v71, v71
	v_fmamk_f32 v72, v72, 0x3e0293ee, v114
	v_add_f32_e32 v115, v68, v115
	v_exp_f32_e32 v72, v72
	s_waitcnt lgkmcnt(6)
	v_mfma_f32_32x32x16_bf16 v[16:31], v[124:127], v[188:191], v[16:31]
	ds_read_b64_tr_b16 v[188:189], v158 offset:0x2400
	ds_read_b64_tr_b16 v[190:191], v158 offset:0x2c00
	v_fmamk_f32 v73, v73, 0x3e0293ee, v114
	v_max3_f32 v112, v112, v74, v75
	v_add_f32_e32 v115, v69, v115
	v_exp_f32_e32 v73, v73
	v_fmamk_f32 v74, v74, 0x3e0293ee, v114
	s_waitcnt lgkmcnt(6)
	v_mfma_f32_32x32x16_bf16 v[0:15], v[124:127], v[192:195], v[0:15]
	ds_read_b64_tr_b16 v[192:193], v158 offset:0x2600
	ds_read_b64_tr_b16 v[194:195], v158 offset:0x2e00
	v_add_f32_e32 v115, v70, v115
	v_exp_f32_e32 v74, v74
	v_fmamk_f32 v75, v75, 0x3e0293ee, v114
	v_max3_f32 v112, v112, v76, v77
	v_add_f32_e32 v115, v71, v115
	s_waitcnt lgkmcnt(6)
	v_mfma_f32_32x32x16_bf16 v[48:63], v[172:175], v[180:183], v[48:63]
	ds_read_b64_tr_b16 v[180:181], v158 offset:0x3000
	ds_read_b64_tr_b16 v[182:183], v158 offset:0x3800
	v_exp_f32_e32 v75, v75
	v_fmamk_f32 v76, v76, 0x3e0293ee, v114
	v_add_f32_e32 v115, v72, v115
	v_exp_f32_e32 v76, v76
	v_fmamk_f32 v77, v77, 0x3e0293ee, v114
	s_waitcnt lgkmcnt(6)
	v_mfma_f32_32x32x16_bf16 v[32:47], v[172:175], v[184:187], v[32:47]
	ds_read_b64_tr_b16 v[184:185], v158 offset:0x3200
	ds_read_b64_tr_b16 v[186:187], v158 offset:0x3a00
	v_max3_f32 v112, v112, v78, v79
	v_add_f32_e32 v115, v73, v115
	v_exp_f32_e32 v77, v77
	v_fmamk_f32 v78, v78, 0x3e0293ee, v114
	v_add_f32_e32 v115, v74, v115
	s_waitcnt lgkmcnt(6)
	v_mfma_f32_32x32x16_bf16 v[16:31], v[172:175], v[188:191], v[16:31]
	ds_read_b64_tr_b16 v[188:189], v158 offset:0x3400
	ds_read_b64_tr_b16 v[190:191], v158 offset:0x3c00
	v_exp_f32_e32 v78, v78
	v_fmac_f32_e32 v114, 0x3e0293ee, v79
	v_add_f32_e32 v115, v75, v115
	v_exp_f32_e32 v79, v114
	v_add_f32_e32 v114, v76, v115
	s_waitcnt lgkmcnt(6)
	v_mfma_f32_32x32x16_bf16 v[0:15], v[172:175], v[192:195], v[0:15]
	ds_read_b64_tr_b16 v[192:193], v158 offset:0x3600
	ds_read_b64_tr_b16 v[194:195], v158 offset:0x3e00
	v_mov_b32_e32 v113, v112
	v_add_f32_e32 v114, v77, v114
	s_nop 0
	v_permlane32_swap_b32_e32 v112, v113
	v_add_f32_e32 v114, v78, v114
	v_add_f32_e32 v120, v79, v114
	v_max_f32_e32 v113, v113, v113
	s_waitcnt lgkmcnt(6)
	v_mfma_f32_32x32x16_bf16 v[48:63], v[168:171], v[180:183], v[48:63]
	v_max_f32_e32 v112, v112, v112
	v_max_f32_e32 v164, v112, v113
	v_mov_b32_e32 v121, v120
	v_cvt_pk_bf16_f32 v112, v64, v65
	v_cvt_pk_bf16_f32 v113, v66, v67
	v_cvt_pk_bf16_f32 v114, v68, v69
	v_cvt_pk_bf16_f32 v115, v70, v71
	s_waitcnt lgkmcnt(4)
	v_mfma_f32_32x32x16_bf16 v[32:47], v[168:171], v[184:187], v[32:47]
	v_cvt_pk_bf16_f32 v116, v72, v73
	v_cvt_pk_bf16_f32 v117, v74, v75
	v_cvt_pk_bf16_f32 v118, v76, v77
	v_cvt_pk_bf16_f32 v119, v78, v79
	s_nop 1
	v_permlane32_swap_b32_e32 v120, v121
	v_permlane32_swap_b32_e32 v112, v114
	s_waitcnt lgkmcnt(2)
	v_mfma_f32_32x32x16_bf16 v[16:31], v[168:171], v[188:191], v[16:31]
	v_permlane32_swap_b32_e32 v113, v115
	v_permlane32_swap_b32_e32 v116, v118
	v_permlane32_swap_b32_e32 v117, v119
	ds_write_b128 v157, v[112:115] offset:4096
	ds_write_b128 v157, v[116:119] offset:5120
	v_add_f32_e32 v120, v120, v121
	v_add_f32_e32 v155, v155, v120
	s_waitcnt lgkmcnt(2)
	v_mfma_f32_32x32x16_bf16 v[0:15], v[168:171], v[192:195], v[0:15]
	s_and_saveexec_b64 s[52:53], s[4:5]
	ds_write_b32 v160, v164 offset:8448
	s_or_b64 exec, exec, s[52:53]
	s_waitcnt vmcnt(0)
	s_waitcnt vmcnt(0) lgkmcnt(0)
	s_barrier
	s_branch .LBB0_748

.Li1_sm:
	ds_read_b64_tr_b16 v[188:189], v158 offset:0x8400
	ds_read_b64_tr_b16 v[190:191], v158 offset:0x8c00
	ds_read_b64_tr_b16 v[192:193], v158 offset:0x8600
	ds_read_b64_tr_b16 v[194:195], v158 offset:0x8e00
	s_waitcnt lgkmcnt(6)
	v_mfma_f32_32x32x16_bf16 v[48:63], v[176:179], v[180:183], v[48:63]
	ds_read_b64_tr_b16 v[180:181], v158 offset:0x9000
	ds_read_b64_tr_b16 v[182:183], v158 offset:0x9800
	v_mul_f32_e32 v114, 0xbe0293ee, v165
	v_max_f32_e32 v112, v65, v65
	v_max_f32_e32 v113, v64, v64
	v_fmamk_f32 v64, v64, 0x3e0293ee, v114
	v_max_f32_e32 v112, v113, v112
	v_exp_f32_e32 v64, v64
	s_waitcnt lgkmcnt(6)
	v_mfma_f32_32x32x16_bf16 v[32:47], v[176:179], v[184:187], v[32:47]
	ds_read_b64_tr_b16 v[184:185], v158 offset:0x9200
	ds_read_b64_tr_b16 v[186:187], v158 offset:0x9a00
	v_fmamk_f32 v65, v65, 0x3e0293ee, v114
	v_max3_f32 v112, v112, v66, v67
	v_exp_f32_e32 v65, v65
	v_fmamk_f32 v66, v66, 0x3e0293ee, v114
	v_exp_f32_e32 v66, v66
	s_waitcnt lgkmcnt(6)
	v_mfma_f32_32x32x16_bf16 v[16:31], v[176:179], v[188:191], v[16:31]
	ds_read_b64_tr_b16 v[188:189], v158 offset:0x9400
	ds_read_b64_tr_b16 v[190:191], v158 offset:0x9c00
	v_fmamk_f32 v67, v67, 0x3e0293ee, v114
	v_max3_f32 v112, v112, v68, v69
	v_exp_f32_e32 v67, v67
	v_fmamk_f32 v68, v68, 0x3e0293ee, v114
	v_add_f32_e32 v115, 0, v64
	s_waitcnt lgkmcnt(6)
	v_mfma_f32_32x32x16_bf16 v[0:15], v[176:179], v[192:195], v[0:15]
	ds_read_b64_tr_b16 v[192:193], v158 offset:0x9600
	ds_read_b64_tr_b16 v[194:195], v158 offset:0x9e00
	v_exp_f32_e32 v68, v68
	v_fmamk_f32 v69, v69, 0x3e0293ee, v114
	v_max3_f32 v112, v112, v70, v71
	v_add_f32_e32 v115, v65, v115
	v_exp_f32_e32 v69, v69
	s_waitcnt lgkmcnt(6)
	v_mfma_f32_32x32x16_bf16 v[48:63], v[168:171], v[180:183], v[48:63]
	ds_read_b64_tr_b16 v[180:181], v158 offset:0xa000
	ds_read_b64_tr_b16 v[182:183], v158 offset:0xa800
	v_fmamk_f32 v70, v70, 0x3e0293ee, v114
	v_add_f32_e32 v115, v66, v115
	v_exp_f32_e32 v70, v70
	v_fmamk_f32 v71, v71, 0x3e0293ee, v114
	v_max3_f32 v112, v112, v72, v73
	s_waitcnt lgkmcnt(6)
	v_mfma_f32_32x32x16_bf16 v[32:47], v[168:171], v[184:187], v[32:47]
	ds_read_b64_tr_b16 v[184:185], v158 offset:0xa200
	ds_read_b64_tr_b16 v[186:187], v158 offset:0xaa00
	v_add_f32_e32 v115, v67, v115
	v_exp_f32_e32 v71, v71
	v_fmamk_f32 v72, v72, 0x3e0293ee, v114
	v_add_f32_e32 v115, v68, v115
	v_exp_f32_e32 v72, v72
	s_waitcnt lgkmcnt(6)
	v_mfma_f32_32x32x16_bf16 v[16:31], v[168:171], v[188:191], v[16:31]
	ds_read_b64_tr_b16 v[188:189], v158 offset:0xa400
	ds_read_b64_tr_b16 v[190:191], v158 offset:0xac00
	v_fmamk_f32 v73, v73, 0x3e0293ee, v114
	v_max3_f32 v112, v112, v74, v75
	v_add_f32_e32 v115, v69, v115
	v_exp_f32_e32 v73, v73
	v_fmamk_f32 v74, v74, 0x3e0293ee, v114
	s_waitcnt lgkmcnt(6)
	v_mfma_f32_32x32x16_bf16 v[0:15], v[168:171], v[192:195], v[0:15]
	ds_read_b64_tr_b16 v[192:193], v158 offset:0xa600
	ds_read_b64_tr_b16 v[194:195], v158 offset:0xae00
	v_add_f32_e32 v115, v70, v115
	v_exp_f32_e32 v74, v74
	v_fmamk_f32 v75, v75, 0x3e0293ee, v114
	v_max3_f32 v112, v112, v76, v77
	v_add_f32_e32 v115, v71, v115
	s_waitcnt lgkmcnt(6)
	v_mfma_f32_32x32x16_bf16 v[48:63], v[172:175], v[180:183], v[48:63]
	ds_read_b64_tr_b16 v[180:181], v158 offset:0xb000
	ds_read_b64_tr_b16 v[182:183], v158 offset:0xb800
	v_exp_f32_e32 v75, v75
	v_fmamk_f32 v76, v76, 0x3e0293ee, v114
	v_add_f32_e32 v115, v72, v115
	v_exp_f32_e32 v76, v76
	v_fmamk_f32 v77, v77, 0x3e0293ee, v114
	s_waitcnt lgkmcnt(6)
	v_mfma_f32_32x32x16_bf16 v[32:47], v[172:175], v[184:187], v[32:47]
	ds_read_b64_tr_b16 v[184:185], v158 offset:0xb200
	ds_read_b64_tr_b16 v[186:187], v158 offset:0xba00
	v_max3_f32 v112, v112, v78, v79
	v_add_f32_e32 v115, v73, v115
	v_exp_f32_e32 v77, v77
	v_fmamk_f32 v78, v78, 0x3e0293ee, v114
	v_add_f32_e32 v115, v74, v115
	s_waitcnt lgkmcnt(6)
	v_mfma_f32_32x32x16_bf16 v[16:31], v[172:175], v[188:191], v[16:31]
	ds_read_b64_tr_b16 v[188:189], v158 offset:0xb400
	ds_read_b64_tr_b16 v[190:191], v158 offset:0xbc00
	v_exp_f32_e32 v78, v78
	v_fmac_f32_e32 v114, 0x3e0293ee, v79
	v_add_f32_e32 v115, v75, v115
	v_exp_f32_e32 v79, v114
	v_add_f32_e32 v114, v76, v115
	s_waitcnt lgkmcnt(6)
	v_mfma_f32_32x32x16_bf16 v[0:15], v[172:175], v[192:195], v[0:15]
	ds_read_b64_tr_b16 v[192:193], v158 offset:0xb600
	ds_read_b64_tr_b16 v[194:195], v158 offset:0xbe00
	v_mov_b32_e32 v113, v112
	v_add_f32_e32 v114, v77, v114
	s_nop 0
	v_permlane32_swap_b32_e32 v112, v113
	v_add_f32_e32 v114, v78, v114
	v_add_f32_e32 v120, v79, v114
	v_max_f32_e32 v113, v113, v113
	s_waitcnt lgkmcnt(6)
	v_mfma_f32_32x32x16_bf16 v[48:63], v[124:127], v[180:183], v[48:63]
	v_max_f32_e32 v112, v112, v112
	v_max_f32_e32 v164, v112, v113
	v_mov_b32_e32 v121, v120
	v_cvt_pk_bf16_f32 v112, v64, v65
	v_cvt_pk_bf16_f32 v113, v66, v67
	v_cvt_pk_bf16_f32 v114, v68, v69
	v_cvt_pk_bf16_f32 v115, v70, v71
	s_waitcnt lgkmcnt(4)
	v_mfma_f32_32x32x16_bf16 v[32:47], v[124:127], v[184:187], v[32:47]
	v_cvt_pk_bf16_f32 v116, v72, v73
	v_cvt_pk_bf16_f32 v117, v74, v75
	v_cvt_pk_bf16_f32 v118, v76, v77
	v_cvt_pk_bf16_f32 v119, v78, v79
	s_nop 1
	v_permlane32_swap_b32_e32 v120, v121
	v_permlane32_swap_b32_e32 v112, v114
	s_waitcnt lgkmcnt(2)
	v_mfma_f32_32x32x16_bf16 v[16:31], v[124:127], v[188:191], v[16:31]
	v_permlane32_swap_b32_e32 v113, v115
	v_permlane32_swap_b32_e32 v116, v118
	v_permlane32_swap_b32_e32 v117, v119
	ds_write_b128 v157, v[112:115]
	ds_write_b128 v157, v[116:119] offset:1024
	v_add_f32_e32 v120, v120, v121
	v_add_f32_e32 v155, v155, v120
	s_waitcnt lgkmcnt(2)
	v_mfma_f32_32x32x16_bf16 v[0:15], v[124:127], v[192:195], v[0:15]
	s_and_saveexec_b64 s[54:55], s[4:5]
	ds_write_b32 v160, v164 offset:8192
	s_or_b64 exec, exec, s[54:55]
	s_waitcnt vmcnt(0)
	s_waitcnt vmcnt(0) lgkmcnt(0)
	s_barrier
	s_branch .LBB0_733
